# P1 K-loop: the duplicate s_waitcnt lgkmcnt(0) after s_setprio 1 deleted in the six phases that already wait right after the barrier
# baseline (speedup 1.0000x reference)
; #define PG8_STAGE(bufoff, gbase, voff) do { _Pragma("unroll") for (int _i = 0; _i < 2; ++_i) { unsigned vo_ = (voff)[_i]; if constexpr (FP8) asm volatile("" : "+v"(vo_)); \
;         __builtin_amdgcn_global_load_lds((const unsigned*)((const char*)(gbase) + vo_), (PG8_LAS unsigned*)(lds + (bufoff) + ldsw + _i * 8192), 16, 0, 0); } } while (0)
; #define PG8_LDA(dst, b, h) do { _Pragma("unroll") for (int m = 0; m < 4; ++m) _Pragma("unroll") for (int k = 0; k < 2; ++k) dst[m][k] = *(const PG8_LAS bf16x8*)(lds + PG8_SA(b, h) + aoff + m * 2048 + k * 1024); } while (0)
; #define PG8_LDB(dst, b, h) do { _Pragma("unroll") for (int n = 0; n < 2; ++n) _Pragma("unroll") for (int k = 0; k < 2; ++k) dst[n][k] = *(const PG8_LAS bf16x8*)(lds + PG8_SB(b, h) + boff + n * 2048 + k * 1024); } while (0)
; #define PG8_WAIT_V(n) asm volatile("s_waitcnt vmcnt(" #n ")" ::: "memory")
; #define PG8_WAIT_L(n) asm volatile("s_waitcnt lgkmcnt(" #n ")" ::: "memory")
; #define PG8_BAR __builtin_amdgcn_s_barrier()
; #define PG8_SCHED __builtin_amdgcn_sched_barrier(0)
; template <class Epi, class Sched, bool ALIGN_EPI = false, bool SP2 = false, bool FP8 = false>
; __device__ __forceinline__ void gemm_phase(PG8_LAS unsigned char* lds, const Gemm g, const Sched& S, const Epi& E) {
;     ...
;             PG8_LDB(B0, 0, 0); PG8_SCHED; PG8_LDA(At, 0, 0); PG8_STAGE(PG8_SA(1, 1), a1 + hstep, voffA);
;             PG8_WAIT_L(8); PG8_BAR; PG8_WAIT_L(0); PG8_MMA(0, 0, At, B0); PG8_BAR; PG8_SCHED;
;             PG8_LDB(B1, 0, 1); PG8_STAGE(PG8_SB(0, 0), b2, voffB);
;             PG8_BAR; PG8_WAIT_L(0); PG8_MMA(0, 1, At, B1); PG8_BAR;
;             PG8_LDA(At, 0, 1); PG8_STAGE(PG8_SA(0, 0), a2, voffA);
;             PG8_BAR; PG8_WAIT_L(0); PG8_MMA(1, 0, At, B0); PG8_BAR; PG8_SCHED;
;             PG8_STAGE(PG8_SB(0, 1), b2 + hstep, voffB);
;             PG8_WAIT_V(6); PG8_BAR; PG8_MMA(1, 1, At, B1); PG8_BAR;
.Lmy_nobar_P1:
.LBB0_102:
	v_add_u32_e32 v140, s87, v160
	ds_read_b128 v[128:131], v140
	ds_read_b128 v[132:135], v140 offset:1024
	ds_read_b128 v[136:139], v140 offset:2048
	ds_read_b128 v[140:143], v140 offset:3072
	s_add_u32 s0, s70, 0xfffe0080
	s_addc_u32 s1, s71, -1
	s_cmp_eq_u32 s94, 4
	s_cselect_b32 s75, s15, s1
	s_cselect_b32 s74, s65, s0
	s_cselect_b32 s73, s63, s93
	s_cselect_b32 s72, s91, s92
	v_mov_b32_e32 v144, v156
	ds_read_b128 v[164:167], v161
	ds_read_b128 v[168:171], v161 offset:1024
	ds_read_b128 v[178:181], v161 offset:2048
	ds_read_b128 v[182:185], v161 offset:3072
	ds_read_b128 v[186:189], v161 offset:4096
	ds_read_b128 v[190:193], v161 offset:5120
	ds_read_b128 v[198:201], v161 offset:6144
	ds_read_b128 v[202:205], v161 offset:7168
	s_add_i32 m0, s77, 0xc000
	s_nop 0
	global_load_lds_dwordx4 v144, s[70:71]
	v_mov_b32_e32 v144, v158
	s_add_i32 m0, s77, 0xe000
	s_nop 0
	global_load_lds_dwordx4 v144, s[70:71]
	s_waitcnt lgkmcnt(8)
	s_barrier
	s_waitcnt lgkmcnt(0)
	s_setprio 1
	v_mfma_scale_f32_16x16x128_f8f6f4 v[124:127], v[128:135], v[164:171], v[124:127], v162, v162 op_sel_hi:[0,0,0]
	v_mfma_scale_f32_16x16x128_f8f6f4 v[120:123], v[136:143], v[164:171], v[120:123], v162, v162 op_sel_hi:[0,0,0]
	v_mfma_scale_f32_16x16x128_f8f6f4 v[150:153], v[128:135], v[178:185], v[108:111], v162, v162 op_sel_hi:[0,0,0]
	v_mfma_scale_f32_16x16x128_f8f6f4 v[172:175], v[136:143], v[178:185], v[104:107], v162, v162 op_sel_hi:[0,0,0]
	v_mfma_scale_f32_16x16x128_f8f6f4 v[206:209], v[128:135], v[186:193], v[92:95], v162, v162 op_sel_hi:[0,0,0]
	v_mfma_scale_f32_16x16x128_f8f6f4 v[210:213], v[136:143], v[186:193], v[88:91], v162, v162 op_sel_hi:[0,0,0]
	v_mfma_scale_f32_16x16x128_f8f6f4 v[214:217], v[128:135], v[198:205], v[76:79], v162, v162 op_sel_hi:[0,0,0]
	v_mfma_scale_f32_16x16x128_f8f6f4 v[218:221], v[136:143], v[198:205], v[72:75], v162, v162 op_sel_hi:[0,0,0]
	s_setprio 0
	s_barrier
	s_nop 1
	v_add_u32_e32 v92, s88, v160
	v_mov_b32_e32 v104, v157
	s_add_i32 s0, s87, s3
	ds_read_b128 v[72:75], v92
	ds_read_b128 v[76:79], v92 offset:1024
	ds_read_b128 v[88:91], v92 offset:2048
	ds_read_b128 v[92:95], v92 offset:3072
	s_mov_b32 m0, s0
	s_nop 0
	global_load_lds_dwordx4 v104, s[72:73]
	v_mov_b32_e32 v104, v159
	s_add_i32 m0, s0, 0x2000
	s_nop 0
	global_load_lds_dwordx4 v104, s[72:73]
	s_barrier
	s_waitcnt lgkmcnt(0)
	s_setprio 1
	v_mfma_scale_f32_16x16x128_f8f6f4 v[116:119], v[72:79], v[164:171], v[116:119], v162, v162 op_sel_hi:[0,0,0]
	v_mfma_scale_f32_16x16x128_f8f6f4 v[112:115], v[88:95], v[164:171], v[112:115], v162, v162 op_sel_hi:[0,0,0]
	v_mfma_scale_f32_16x16x128_f8f6f4 v[164:167], v[72:79], v[178:185], v[100:103], v162, v162 op_sel_hi:[0,0,0]
	v_mfma_scale_f32_16x16x128_f8f6f4 v[168:171], v[88:95], v[178:185], v[96:99], v162, v162 op_sel_hi:[0,0,0]
	v_mfma_scale_f32_16x16x128_f8f6f4 v[178:181], v[72:79], v[186:193], v[84:87], v162, v162 op_sel_hi:[0,0,0]
	v_mfma_scale_f32_16x16x128_f8f6f4 v[182:185], v[88:95], v[186:193], v[80:83], v162, v162 op_sel_hi:[0,0,0]
	v_mfma_scale_f32_16x16x128_f8f6f4 v[186:189], v[72:79], v[198:205], v[68:71], v162, v162 op_sel_hi:[0,0,0]
	v_mfma_scale_f32_16x16x128_f8f6f4 v[190:193], v[88:95], v[198:205], v[64:67], v162, v162 op_sel_hi:[0,0,0]
	s_setprio 0
	v_mov_b32_e32 v144, v156
	s_mov_b32 m0, s77
	s_barrier
	s_nop 2
	ds_read_b128 v[64:67], v161 offset:16384
	ds_read_b128 v[68:71], v161 offset:17408
	ds_read_b128 v[80:83], v161 offset:18432
	ds_read_b128 v[84:87], v161 offset:19456
	ds_read_b128 v[96:99], v161 offset:20480
	ds_read_b128 v[100:103], v161 offset:21504
	ds_read_b128 v[104:107], v161 offset:22528
	ds_read_b128 v[108:111], v161 offset:23552
	s_nop 0
	global_load_lds_dwordx4 v144, s[74:75]
	v_mov_b32_e32 v144, v158
	s_mov_b32 m0, s78
	s_nop 0
	global_load_lds_dwordx4 v144, s[74:75]
	s_barrier
	s_waitcnt lgkmcnt(0)
	s_setprio 1
	v_mfma_scale_f32_16x16x128_f8f6f4 v[60:63], v[128:135], v[64:71], v[60:63], v162, v162 op_sel_hi:[0,0,0]
	v_mfma_scale_f32_16x16x128_f8f6f4 v[56:59], v[136:143], v[64:71], v[56:59], v162, v162 op_sel_hi:[0,0,0]
	v_mfma_scale_f32_16x16x128_f8f6f4 v[198:201], v[128:135], v[80:87], v[44:47], v162, v162 op_sel_hi:[0,0,0]
	v_mfma_scale_f32_16x16x128_f8f6f4 v[202:205], v[136:143], v[80:87], v[40:43], v162, v162 op_sel_hi:[0,0,0]
	v_mfma_scale_f32_16x16x128_f8f6f4 v[222:225], v[128:135], v[96:103], v[28:31], v162, v162 op_sel_hi:[0,0,0]
	v_mfma_scale_f32_16x16x128_f8f6f4 v[226:229], v[136:143], v[96:103], v[24:27], v162, v162 op_sel_hi:[0,0,0]
	v_mfma_scale_f32_16x16x128_f8f6f4 v[230:233], v[128:135], v[104:111], v[12:15], v162, v162 op_sel_hi:[0,0,0]
	v_mfma_scale_f32_16x16x128_f8f6f4 v[234:237], v[136:143], v[104:111], v[8:11], v162, v162 op_sel_hi:[0,0,0]
	s_setprio 0
	s_barrier
	s_add_u32 s0, s72, 0x20000
	s_addc_u32 s1, s73, 0
	s_nop 2
	v_mov_b32_e32 v8, v157
	s_add_i32 s95, s88, s3
	s_mov_b32 m0, s95
	s_nop 0
	global_load_lds_dwordx4 v8, s[0:1]
	v_mov_b32_e32 v8, v159
	s_add_i32 m0, s95, 0x2000
	s_nop 0
	global_load_lds_dwordx4 v8, s[0:1]
	s_waitcnt vmcnt(6)
	s_barrier
	s_setprio 1
	v_mfma_scale_f32_16x16x128_f8f6f4 v[52:55], v[72:79], v[64:71], v[52:55], v162, v162 op_sel_hi:[0,0,0]
	v_mfma_scale_f32_16x16x128_f8f6f4 v[48:51], v[88:95], v[64:71], v[48:51], v162, v162 op_sel_hi:[0,0,0]
	v_mfma_scale_f32_16x16x128_f8f6f4 v[238:241], v[72:79], v[80:87], v[36:39], v162, v162 op_sel_hi:[0,0,0]
	v_mfma_scale_f32_16x16x128_f8f6f4 v[242:245], v[88:95], v[80:87], v[32:35], v162, v162 op_sel_hi:[0,0,0]
	v_mfma_scale_f32_16x16x128_f8f6f4 v[246:249], v[72:79], v[96:103], v[20:23], v162, v162 op_sel_hi:[0,0,0]
	v_mfma_scale_f32_16x16x128_f8f6f4 v[250:253], v[88:95], v[96:103], v[16:19], v162, v162 op_sel_hi:[0,0,0]
	v_mfma_scale_f32_16x16x128_f8f6f4 v[194:197], v[72:79], v[104:111], v[4:7], v162, v162 op_sel_hi:[0,0,0]
	v_mfma_scale_f32_16x16x128_f8f6f4 v[146:149], v[88:95], v[104:111], v[0:3], v162, v162 op_sel_hi:[0,0,0]
	s_setprio 0
	s_add_i32 s95, 0, 0x18000
	v_add_u32_e32 v8, s95, v160
	s_barrier
; #define PG8_STAGE(bufoff, gbase, voff) do { _Pragma("unroll") for (int _i = 0; _i < 2; ++_i) { unsigned vo_ = (voff)[_i]; if constexpr (FP8) asm volatile("" : "+v"(vo_)); \
;         __builtin_amdgcn_global_load_lds((const unsigned*)((const char*)(gbase) + vo_), (PG8_LAS unsigned*)(lds + (bufoff) + ldsw + _i * 8192), 16, 0, 0); } } while (0)
; #define PG8_LDA(dst, b, h) do { _Pragma("unroll") for (int m = 0; m < 4; ++m) _Pragma("unroll") for (int k = 0; k < 2; ++k) dst[m][k] = *(const PG8_LAS bf16x8*)(lds + PG8_SA(b, h) + aoff + m * 2048 + k * 1024); } while (0)
; #define PG8_LDB(dst, b, h) do { _Pragma("unroll") for (int n = 0; n < 2; ++n) _Pragma("unroll") for (int k = 0; k < 2; ++k) dst[n][k] = *(const PG8_LAS bf16x8*)(lds + PG8_SB(b, h) + boff + n * 2048 + k * 1024); } while (0)
; #define PG8_WAIT_V(n) asm volatile("s_waitcnt vmcnt(" #n ")" ::: "memory")
; #define PG8_WAIT_L(n) asm volatile("s_waitcnt lgkmcnt(" #n ")" ::: "memory")
; #define PG8_BAR __builtin_amdgcn_s_barrier()
; #define PG8_SCHED __builtin_amdgcn_sched_barrier(0)
; template <class Epi, class Sched, bool ALIGN_EPI = false, bool SP2 = false, bool FP8 = false>
; __device__ __forceinline__ void gemm_phase(PG8_LAS unsigned char* lds, const Gemm g, const Sched& S, const Epi& E) {
;     ...
;             PG8_LDB(B0, 1, 0); PG8_SCHED; PG8_LDA(At, 1, 0); PG8_STAGE(PG8_SA(0, 1), a2 + hstep, voffA);
;             PG8_WAIT_L(8); PG8_BAR; PG8_WAIT_L(0); PG8_MMA(0, 0, At, B0); PG8_BAR; PG8_SCHED;
;             PG8_LDB(B1, 1, 1); PG8_STAGE(PG8_SB(1, 0), b3, voffB);
;             PG8_BAR; PG8_WAIT_L(0); PG8_MMA(0, 1, At, B1); PG8_BAR;
;             PG8_LDA(At, 1, 1); PG8_STAGE(PG8_SA(1, 0), a3, voffA);
;             PG8_BAR; PG8_WAIT_L(0); PG8_MMA(1, 0, At, B0); PG8_BAR; PG8_SCHED;
;             PG8_STAGE(PG8_SB(1, 1), b3 + hstep, voffB);
;             PG8_WAIT_V(6); PG8_BAR; PG8_MMA(1, 1, At, B1); PG8_BAR;
	s_nop 2
	ds_read_b128 v[0:3], v8
	ds_read_b128 v[4:7], v8 offset:1024
	ds_read_b128 v[16:19], v8 offset:2048
	ds_read_b128 v[20:23], v8 offset:3072
	s_add_u32 s0, s74, 0x20000
	v_mov_b32_e32 v64, v156
	s_mov_b32 m0, s79
	ds_read_b128 v[8:11], v161 offset:32768
	ds_read_b128 v[12:15], v161 offset:33792
	ds_read_b128 v[24:27], v161 offset:34816
	ds_read_b128 v[28:31], v161 offset:35840
	ds_read_b128 v[32:35], v161 offset:36864
	ds_read_b128 v[36:39], v161 offset:37888
	ds_read_b128 v[40:43], v161 offset:38912
	ds_read_b128 v[44:47], v161 offset:39936
	s_addc_u32 s1, s75, 0
	s_nop 0
	global_load_lds_dwordx4 v64, s[0:1]
	v_mov_b32_e32 v64, v158
	s_mov_b32 m0, s80
	s_nop 0
	global_load_lds_dwordx4 v64, s[0:1]
	s_waitcnt lgkmcnt(8)
	s_barrier
	s_waitcnt lgkmcnt(0)
	s_setprio 1
	v_mfma_scale_f32_16x16x128_f8f6f4 v[124:127], v[0:7], v[8:15], v[124:127], v162, v162 op_sel_hi:[0,0,0]
	v_mfma_scale_f32_16x16x128_f8f6f4 v[120:123], v[16:23], v[8:15], v[120:123], v162, v162 op_sel_hi:[0,0,0]
	v_mfma_scale_f32_16x16x128_f8f6f4 v[108:111], v[0:7], v[24:31], v[150:153], v162, v162 op_sel_hi:[0,0,0]
	v_mfma_scale_f32_16x16x128_f8f6f4 v[104:107], v[16:23], v[24:31], v[172:175], v162, v162 op_sel_hi:[0,0,0]
	v_mfma_scale_f32_16x16x128_f8f6f4 v[92:95], v[0:7], v[32:39], v[206:209], v162, v162 op_sel_hi:[0,0,0]
	v_mfma_scale_f32_16x16x128_f8f6f4 v[88:91], v[16:23], v[32:39], v[210:213], v162, v162 op_sel_hi:[0,0,0]
	v_mfma_scale_f32_16x16x128_f8f6f4 v[76:79], v[0:7], v[40:47], v[214:217], v162, v162 op_sel_hi:[0,0,0]
	v_mfma_scale_f32_16x16x128_f8f6f4 v[72:75], v[16:23], v[40:47], v[218:221], v162, v162 op_sel_hi:[0,0,0]
	s_setprio 0
	s_barrier
	s_add_i32 s96, 0, 0x1c000
	v_add_u32_e32 v64, s96, v160
	v_mov_b32_e32 v144, v157
	ds_read_b128 v[128:131], v64
	ds_read_b128 v[132:135], v64 offset:1024
	ds_read_b128 v[136:139], v64 offset:2048
	ds_read_b128 v[140:143], v64 offset:3072
	s_add_i32 s0, s95, s3
	v_lshl_add_u64 v[64:65], s[72:73], 0, v[144:145]
	v_lshl_add_u64 v[64:65], v[64:65], 0, s[8:9]
	s_mov_b32 m0, s0
	v_mov_b32_e32 v144, v159
	global_load_lds_dwordx4 v[64:65], off
	s_add_i32 m0, s0, 0x2000
	v_lshl_add_u64 v[64:65], s[72:73], 0, v[144:145]
	v_lshl_add_u64 v[64:65], v[64:65], 0, s[8:9]
	global_load_lds_dwordx4 v[64:65], off
	s_barrier
	s_waitcnt lgkmcnt(0)
	s_setprio 1
	v_mfma_scale_f32_16x16x128_f8f6f4 v[116:119], v[128:135], v[8:15], v[116:119], v162, v162 op_sel_hi:[0,0,0]
	v_mfma_scale_f32_16x16x128_f8f6f4 v[112:115], v[136:143], v[8:15], v[112:115], v162, v162 op_sel_hi:[0,0,0]
	v_mfma_scale_f32_16x16x128_f8f6f4 v[100:103], v[128:135], v[24:31], v[164:167], v162, v162 op_sel_hi:[0,0,0]
	v_mfma_scale_f32_16x16x128_f8f6f4 v[96:99], v[136:143], v[24:31], v[168:171], v162, v162 op_sel_hi:[0,0,0]
	v_mfma_scale_f32_16x16x128_f8f6f4 v[84:87], v[128:135], v[32:39], v[178:181], v162, v162 op_sel_hi:[0,0,0]
	v_mfma_scale_f32_16x16x128_f8f6f4 v[80:83], v[136:143], v[32:39], v[182:185], v162, v162 op_sel_hi:[0,0,0]
	v_mfma_scale_f32_16x16x128_f8f6f4 v[68:71], v[128:135], v[40:47], v[186:189], v162, v162 op_sel_hi:[0,0,0]
	v_mfma_scale_f32_16x16x128_f8f6f4 v[64:67], v[136:143], v[40:47], v[190:193], v162, v162 op_sel_hi:[0,0,0]
	s_setprio 0
	v_mov_b32_e32 v144, v156
	s_barrier
	ds_read_b128 v[32:35], v161 offset:49152
	ds_read_b128 v[36:39], v161 offset:50176
	ds_read_b128 v[164:167], v161 offset:51200
	ds_read_b128 v[168:171], v161 offset:52224
	ds_read_b128 v[178:181], v161 offset:53248
	ds_read_b128 v[182:185], v161 offset:54272
	ds_read_b128 v[186:189], v161 offset:55296
	ds_read_b128 v[190:193], v161 offset:56320
	s_mov_b32 m0, s83
	v_lshl_add_u64 v[8:9], s[74:75], 0, v[144:145]
	v_lshl_add_u64 v[8:9], v[8:9], 0, s[8:9]
	v_mov_b32_e32 v144, v158
	global_load_lds_dwordx4 v[8:9], off
	s_mov_b32 m0, s84
	v_lshl_add_u64 v[8:9], s[74:75], 0, v[144:145]
	v_lshl_add_u64 v[8:9], v[8:9], 0, s[8:9]
	global_load_lds_dwordx4 v[8:9], off
	s_barrier
	s_waitcnt lgkmcnt(0)
	s_setprio 1
	v_mfma_scale_f32_16x16x128_f8f6f4 v[60:63], v[0:7], v[32:39], v[60:63], v162, v162 op_sel_hi:[0,0,0]
	v_mfma_scale_f32_16x16x128_f8f6f4 v[56:59], v[16:23], v[32:39], v[56:59], v162, v162 op_sel_hi:[0,0,0]
	v_mfma_scale_f32_16x16x128_f8f6f4 v[44:47], v[0:7], v[164:171], v[198:201], v162, v162 op_sel_hi:[0,0,0]
	v_mfma_scale_f32_16x16x128_f8f6f4 v[40:43], v[16:23], v[164:171], v[202:205], v162, v162 op_sel_hi:[0,0,0]
	v_mfma_scale_f32_16x16x128_f8f6f4 v[28:31], v[0:7], v[178:185], v[222:225], v162, v162 op_sel_hi:[0,0,0]
	v_mfma_scale_f32_16x16x128_f8f6f4 v[24:27], v[16:23], v[178:185], v[226:229], v162, v162 op_sel_hi:[0,0,0]
	v_mfma_scale_f32_16x16x128_f8f6f4 v[12:15], v[0:7], v[186:193], v[230:233], v162, v162 op_sel_hi:[0,0,0]
	v_mfma_scale_f32_16x16x128_f8f6f4 v[8:11], v[16:23], v[186:193], v[234:237], v162, v162 op_sel_hi:[0,0,0]
	s_setprio 0
	s_barrier
	s_add_u32 s0, s72, 0x20080
	s_addc_u32 s1, s73, 0
	v_mov_b32_e32 v0, v157
	s_add_i32 s72, s96, s3
	s_mov_b32 m0, s72
	s_nop 0
	global_load_lds_dwordx4 v0, s[0:1]
	v_mov_b32_e32 v0, v159
	s_add_i32 m0, s72, 0x2000
	s_nop 0
	global_load_lds_dwordx4 v0, s[0:1]
	s_waitcnt vmcnt(6)
	s_barrier
	s_setprio 1
	v_mfma_scale_f32_16x16x128_f8f6f4 v[52:55], v[128:135], v[32:39], v[52:55], v162, v162 op_sel_hi:[0,0,0]
	v_mfma_scale_f32_16x16x128_f8f6f4 v[48:51], v[136:143], v[32:39], v[48:51], v162, v162 op_sel_hi:[0,0,0]
	v_mfma_scale_f32_16x16x128_f8f6f4 v[36:39], v[128:135], v[164:171], v[238:241], v162, v162 op_sel_hi:[0,0,0]
	v_mfma_scale_f32_16x16x128_f8f6f4 v[32:35], v[136:143], v[164:171], v[242:245], v162, v162 op_sel_hi:[0,0,0]
	v_mfma_scale_f32_16x16x128_f8f6f4 v[20:23], v[128:135], v[178:185], v[246:249], v162, v162 op_sel_hi:[0,0,0]
	v_mfma_scale_f32_16x16x128_f8f6f4 v[16:19], v[136:143], v[178:185], v[250:253], v162, v162 op_sel_hi:[0,0,0]
	v_mfma_scale_f32_16x16x128_f8f6f4 v[4:7], v[128:135], v[186:193], v[194:197], v162, v162 op_sel_hi:[0,0,0]
	v_mfma_scale_f32_16x16x128_f8f6f4 v[0:3], v[136:143], v[186:193], v[146:149], v162, v162 op_sel_hi:[0,0,0]
	s_setprio 0
	s_add_i32 s94, s94, 2
	s_add_u32 s70, s70, 0x100
	s_addc_u32 s71, s71, 0
	s_add_u32 s92, s92, 0x100
	s_addc_u32 s93, s93, 0
	s_cmp_gt_u32 s94, 5
	s_barrier
	s_cbranch_scc0 .LBB0_102
	s_and_b64 vcc, exec, s[44:45]
	s_cbranch_vccz .LBB0_105
	s_barrier
